# local-barrier guard additionally requires gridDim.x to be a multiple of 8 (robustness; no intended timing change)
# baseline (speedup 1.0000x reference)
; #define PG8_STAGE(bufoff, gbase, voff) do { _Pragma("unroll") for (int _i = 0; _i < 2; ++_i) \
;         __builtin_amdgcn_global_load_lds((const unsigned*)((const char*)(gbase) + (voff)[_i]), (PG8_LAS unsigned*)(lds + (bufoff) + ldsw + _i * 8192), 16, 0, 0); } while (0)
; #define PG8_BAR __builtin_amdgcn_s_barrier()
; template <class Epi, class Sched, bool ALIGN_EPI = false, bool SP2 = false>
; __device__ __forceinline__ void gemm_phase(PG8_LAS unsigned char* lds, const Gemm g, const Sched& S, const Epi& E) {
;     int tid = threadIdx.x; asm volatile("" : "+v"(tid));
;     const int wid = __builtin_amdgcn_readfirstlane(tid >> 6), lane = tid & 63, wr = wid >> 2, wc = wid & 3, fr = lane & 15, fq = lane >> 4;
;     const int K = g.K, nt = K / BK;
;     unsigned voffA[2], voffB[2];
; #pragma unroll
;     for (int i = 0; i < 2; ++i) { int R, C; stage_rc(tid * 16 + i * 8192, R, C); const int Rb = Epi::PERM ? ((R & ~31) + perm32(R & 31)) : R;
;         voffA[i] = (unsigned)(R * K + C) * 2u; voffB[i] = (unsigned)(Rb * K + C) * 2u; }
;     const size_t kstep = (size_t)(BK * 2);
;     const size_t hstep = (size_t)HALF * K * 2;
;     const size_t tstep = 2 * hstep;
;     const unsigned ldsw = (unsigned)wid * 1024u;
;     const int aoff = lds_byte(wr * 64 + fr, fq * 8), boff = lds_byte(wc * 32 + fr, fq * 8);
;     ...
;     Unit cur, nxt; int ui = 0;
;     if (!S.next(0, cur)) return;
;     f32x4 acc[2][2][4][2];
; #pragma unroll
;     for (int a = 0; a < 2; ++a)
; #pragma unroll
;         for (int b = 0; b < 2; ++b)
; #pragma unroll
;             for (int m = 0; m < 4; ++m)
; #pragma unroll
;                 for (int n = 0; n < 2; ++n) acc[a][b][m][n] = (f32x4){0.f, 0.f, 0.f, 0.f};
;     bf16x8 At[4][2], B0[2][2], B1[2][2];
;     const char* cA = (const char*)g.A + (size_t)cur.pm * tstep; const char* cB = (const char*)g.Bt + (size_t)cur.pn * tstep;
;     S.a_ready(cur);
;     if constexpr (SP2) {
;         PG8_STAGE(PG8_SB(0, 0), cB, voffB); PG8_STAGE(PG8_SB(0, 1), cB + hstep, voffB); PG8_STAGE(PG8_SA(0, 0), cA, voffA); PG8_STAGE(PG8_SA(0, 1), cA + hstep, voffA);
;         if (wr == 1) PG8_BAR;
.LBB0_183:
	s_or_b64 exec, exec, s[0:1]
	v_readlane_b32 s4, v235, 8
	v_readlane_b32 s5, v235, 9
	v_and_b32_e32 v0, 7, v189
	v_lshlrev_b32_e32 v0, 3, v0
	v_add_u32_e32 v0, 0x3800, v0
	s_nop 1
	global_load_dwordx2 v[0:1], v0, s[4:5] sc1
	s_waitcnt vmcnt(0)
	v_add_u32_e32 v0, v0, v1
	v_cmp_ne_u32_e32 vcc, 17, v0
	s_cmp_lg_u64 vcc, 0
	s_cselect_b32 s4, 1, 0
	v_readlane_b32 s5, v235, 6
	s_nop 0
	s_and_b32 s5, s5, 7
	s_or_b32 s4, s4, s5
	v_mov_b32_e32 v0, 0x20170
	v_mov_b32_e32 v1, s4
	ds_write_b32 v0, v1
	v_readlane_b32 s0, v235, 2
	v_readlane_b32 s2, v235, 4
	v_readlane_b32 s1, v235, 3
	v_readlane_b32 s3, v235, 5
	s_add_u32 s0, s2, 0x7000000
	s_addc_u32 s1, s3, 0
	v_writelane_b32 v235, s0, 33
	v_mov_b32_e32 v9, v189
	s_waitcnt lgkmcnt(0)
	v_writelane_b32 v235, s1, 34
	s_barrier
	v_readlane_b32 s0, v235, 0
	s_cmpk_lt_i32 s0, 0xb00
	s_cselect_b64 s[2:3], -1, 0
	v_writelane_b32 v235, s2, 35
	s_cmpk_gt_i32 s0, 0xaff
	v_readfirstlane_b32 s1, v9
	v_writelane_b32 v235, s3, 36
	s_cbranch_scc1 .LBB0_199
	v_lshlrev_b32_e32 v0, 4, v9
	v_add_u32_e32 v1, 0x2000, v0
	v_ashrrev_i32_e32 v2, 31, v1
	v_lshrrev_b32_e32 v2, 22, v2
	v_add_u32_e32 v2, v1, v2
	v_ashrrev_i32_e32 v8, 10, v2
	v_mul_i32_i24_e32 v2, 0x400, v8
	v_sub_u32_e32 v1, v1, v2
	v_lshrrev_b32_e32 v2, 4, v1
	v_bitop3_b32 v1, v2, v1, 32 bitop3:0x6c
	v_ashrrev_i32_e32 v2, 31, v1
	v_lshrrev_b32_e32 v2, 26, v2
	v_add_u32_e32 v2, v1, v2
	v_lshlrev_b32_e32 v3, 3, v8
	v_ashrrev_i32_e32 v10, 6, v2
	v_and_b32_e32 v3, -16, v3
	v_add_u32_e32 v3, v10, v3
	v_and_b32_e32 v4, 3, v10
	s_mov_b32 s0, 0x1fffe0
	v_lshrrev_b32_e32 v5, 2, v3
	v_lshlrev_b32_e32 v6, 1, v3
	v_and_b32_e32 v2, 0xc0, v2
	v_and_or_b32 v4, v3, s0, v4
	v_and_b32_e32 v5, 4, v5
	v_and_b32_e32 v6, 24, v6
	v_sub_u32_e32 v1, v1, v2
	v_mov_b32_e32 v2, 1
	v_or3_b32 v4, v4, v5, v6
	v_lshlrev_b32_e32 v5, 5, v8
	v_ashrrev_i16_sdwa v1, v2, sext(v1) dst_sel:DWORD dst_unused:UNUSED_PAD src0_sel:DWORD src1_sel:BYTE_0
	v_and_b32_e32 v5, 32, v5
	v_bfe_i32 v11, v1, 0, 16
	v_add_lshl_u32 v1, v5, v11, 1
	v_lshl_add_u32 v128, v4, 11, v1
	v_lshl_add_u32 v130, v3, 11, v1
	v_bfe_i32 v1, v9, 27, 1
	v_lshrrev_b32_e32 v1, 22, v1
	v_add_u32_e32 v1, v0, v1
	v_and_b32_e32 v1, 0xfffffc00, v1
	v_sub_u32_e32 v0, v0, v1
	v_lshrrev_b32_e32 v1, 4, v0
	v_ashrrev_i32_e32 v3, 31, v9
	v_bitop3_b32 v0, v1, v0, 32 bitop3:0x6c
	v_lshrrev_b32_e32 v3, 26, v3
	v_ashrrev_i32_e32 v1, 31, v0
	v_add_u32_e32 v3, v9, v3
	v_readlane_b32 s4, v235, 2
	v_lshrrev_b32_e32 v1, 26, v1
	v_ashrrev_i32_e32 v13, 6, v3
	v_readlane_b32 s6, v235, 4
	v_add_u32_e32 v1, v0, v1
	v_lshlrev_b32_e32 v3, 3, v13
	v_readlane_b32 s7, v235, 5
	s_add_u32 s33, s6, 0x200000
	v_ashrrev_i32_e32 v12, 6, v1
	v_and_b32_e32 v3, -16, v3
	v_readlane_b32 s3, v235, 0
	s_addc_u32 s34, s7, 0
	v_add_u32_e32 v3, v12, v3
	v_and_b32_e32 v4, 3, v12
	s_ashr_i32 s36, s3, 31
	v_and_or_b32 v4, v3, s0, v4
	s_lshr_b32 s0, s36, 29
	s_add_i32 s0, s3, s0
	s_ashr_i32 s4, s1, 6
	s_ashr_i32 s2, s0, 3
	s_and_b32 s0, s0, -8
	s_ashr_i32 s6, s1, 8
	s_lshl_b32 s35, s4, 10
	s_sub_i32 s0, s3, s0
	s_cmp_lt_i32 s0, 0
	s_movk_i32 s37, 0x161
	s_cselect_b32 s3, s37, 0x160
	s_mul_i32 s0, s0, s3
	s_add_i32 s0, s0, s2
	s_mul_hi_i32 s2, s0, 0x2e8ba2e9
	s_lshr_b32 s3, s2, 31
	s_ashr_i32 s2, s2, 4
	s_add_i32 s2, s2, s3
	s_lshl_b32 s3, s2, 2
	s_mulk_i32 s2, 0x58
	s_sub_i32 s2, s0, s2
	s_bfe_i32 s0, s2, 0x80000
	v_readlane_b32 s5, v235, 3
	s_bfe_u32 s0, s0, 0x2000d
	s_add_i32 s5, s2, s0
	s_bfe_i32 s0, s5, 0x80000
	s_and_b32 s5, s5, 0xfc
	s_sub_i32 s2, s2, s5
	s_sext_i32_i16 s0, s0
	s_sext_i32_i8 s2, s2
	v_lshrrev_b32_e32 v5, 2, v3
	v_lshlrev_b32_e32 v6, 1, v3
	v_and_b32_e32 v1, 0xc0, v1
	s_lshr_b32 s0, s0, 2
	s_add_i32 s20, s3, s2
	v_and_b32_e32 v5, 4, v5
	v_and_b32_e32 v6, 24, v6
	v_sub_u32_e32 v0, v0, v1
	s_ashr_i32 s21, s20, 31
	s_bfe_i64 s[8:9], s[0:1], 0x100000
	v_or3_b32 v4, v4, v5, v6
	v_lshlrev_b32_e32 v5, 5, v13
	v_ashrrev_i16_sdwa v0, v2, sext(v0) dst_sel:DWORD dst_unused:UNUSED_PAD src0_sel:DWORD src1_sel:BYTE_0
	s_lshl_b64 s[2:3], s[20:21], 19
	s_lshl_b64 s[8:9], s[8:9], 19
	v_and_b32_e32 v5, 32, v5
	v_bfe_i32 v14, v0, 0, 16
	s_add_u32 s24, s33, s8
	v_add_lshl_u32 v0, v5, v14, 1
	s_addc_u32 s25, s34, s9
	s_add_i32 s21, s35, 0
	v_lshl_add_u32 v132, v4, 11, v0
	s_add_i32 m0, s21, 0x10000
	v_lshl_add_u32 v134, v3, 11, v0
	global_load_lds_dwordx4 v132, s[24:25]
	s_add_i32 m0, s21, 0x12000
	s_add_u32 s8, s24, 0x40000
	global_load_lds_dwordx4 v128, s[24:25]
	s_addc_u32 s9, s25, 0
	s_add_i32 m0, s21, 0x14000
	v_mov_b32_e32 v133, 0
	global_load_lds_dwordx4 v132, s[8:9]
	s_add_i32 m0, s21, 0x16000
	v_mov_b32_e32 v129, v133
	global_load_lds_dwordx4 v128, s[8:9]
	v_readlane_b32 s8, v235, 31
	v_readlane_b32 s9, v235, 32
	s_add_u32 s22, s8, s2
	s_addc_u32 s23, s9, s3
	s_add_i32 s38, s21, 0x2000
	s_mov_b32 m0, s21
	s_add_u32 s2, s22, 0x40000
	global_load_lds_dwordx4 v134, s[22:23]
	s_mov_b32 m0, s38
	s_addc_u32 s3, s23, 0
	s_add_i32 s39, s21, 0x4000
	global_load_lds_dwordx4 v130, s[22:23]
	s_mov_b32 m0, s39
	s_add_i32 s40, s21, 0x6000
	global_load_lds_dwordx4 v134, s[2:3]
	s_mov_b32 m0, s40
	v_mov_b32_e32 v135, v133
	global_load_lds_dwordx4 v130, s[2:3]
	v_mov_b32_e32 v131, v133
	s_cmp_eq_u32 s6, 1
	s_mov_b32 s41, 0
	v_lshl_add_u64 v[6:7], s[24:25], 0, v[132:133]
	v_lshl_add_u64 v[4:5], s[24:25], 0, v[128:129]
	v_lshl_add_u64 v[0:1], s[22:23], 0, v[134:135]
	s_cselect_b64 s[2:3], -1, 0
	s_cmp_lg_u32 s6, 1
	v_lshl_add_u64 v[2:3], s[22:23], 0, v[130:131]
	s_cbranch_scc1 .LBB0_186
	s_barrier
